# attention fast loop placed at a better code alignment (unreachable padding before/after the hand-written region)
# baseline (speedup 1.0000x reference)
.LBB0_867:
	s_andn2_b64 vcc, exec, s[10:11]
	s_cbranch_vccnz .LBB0_852
	s_lshl_b32 s10, s26, 14
	s_addk_i32 s10, 0x4000
	s_cmp_lg_u32 s26, 2
	s_cselect_b32 s10, s10, 0
	s_add_i32 s22, s52, s10
	s_mov_b64 s[10:11], 0x61e8c100
	v_lshl_add_u64 v[80:81], v[178:179], 0, s[10:11]
	s_mov_b32 m0, s22
	s_mov_b64 s[10:11], 0x61e8c180
	global_load_lds_dwordx4 v[80:81], off
	v_lshl_add_u64 v[80:81], v[178:179], 0, s[10:11]
	s_add_i32 m0, s22, 0x400
	s_nop 0
	global_load_lds_dwordx4 v[80:81], off
	s_branch .LBB0_852
	s_nop 0
	s_nop 0
	s_nop 0
	s_nop 0
	s_nop 0
	s_nop 0
	s_nop 0
	s_nop 0

; __device__ __forceinline__ void finishSM_fix(f32x16& p0, f32x16& p1, float& l_lane, bf16x8& pa0, bf16x8& pa1, bf16x8& pa2, bf16x8& pa3) {
; #pragma unroll
;   for (int r = 0; r < 16; ++r) p1[r] = __builtin_amdgcn_exp2f(p1[r]);
;   float ps = 0;
; #pragma unroll
;   for (int r = 0; r < 16; ++r) ps += p0[r];
; #pragma unroll
;   for (int r = 0; r < 16; ++r) ps += p1[r];
;   l_lane += ps;
;     ...
;   PK4(p0, 0, pa0); PK4(p0, 8, pa1); PK4(p1, 0, pa2); PK4(p1, 8, pa3);
; __device__ __forceinline__ void qkt12(f32x16& p0, f32x16& p1, const char* Ks, const bf16x8 (&qr)[12], const int (&kb)[4]) {
;   p0 = f32x16{}; p1 = f32x16{};
;     ...
;   bf16x8 c0 = KLD(0, 0), c1 = KLD(0, 1);
; #pragma unroll
;   for (int d0 = 0; d0 < 12; ++d0) {
;     bf16x8 n0 = c0, n1 = c1;
;     if (d0 < 11) { n0 = KLD(d0 + 1, 0); n1 = KLD(d0 + 1, 1); }
;     __builtin_amdgcn_sched_group_barrier(0x100, 2, 0);
;     p0 = __builtin_amdgcn_mfma_f32_32x32x16_bf16(c0, qr[d0], p0, 0, 0, 0);
;     p1 = __builtin_amdgcn_mfma_f32_32x32x16_bf16(c1, qr[d0], p1, 0, 0, 0);
;     __builtin_amdgcn_sched_group_barrier(0x008, 2, 0);
;     c0 = n0; c1 = n1; }
;     ...
; }
.Lfa_loop:
	s_add_i32 s22, s26, 1
	s_cmp_lg_u32 s26, 2
	s_cselect_b32 s24, s22, 0
	s_add_i32 s22, s24, 1
	s_cmp_lg_u32 s24, 2
	s_cselect_b32 s25, s22, 0
	s_waitcnt vmcnt(5)
	s_barrier
	s_mul_i32 s6, s24, 0x6000
	s_mul_i32 s10, s26, 0x6000
	s_lshl_b32 s11, s25, 14
	s_add_i32 s10, s43, s10
	s_add_i32 s11, s52, s11
	v_add_u32_e32 v187, s6, v183
	v_add_u32_e32 v188, s6, v184
	v_add_u32_e32 v189, s6, v185
	v_add_u32_e32 v190, s6, v186
	v_lshl_add_u32 v191, s26, 14, v182
	ds_read_b128 v[172:175], v187
	ds_read_b128 v[176:179], v187 offset:12288
	ds_read_b128 v[200:203], v188
	ds_read_b128 v[204:207], v188 offset:12288
	v_add_f32_e32 v196, v82, v83
	v_cvt_pk_bf16_f32 v82, v82, v83
	v_add_f32_e32 v197, v84, v85
	v_exp_f32_e32 v66, v66
	v_exp_f32_e32 v67, v67
	v_cvt_pk_bf16_f32 v83, v84, v85
	v_add_f32_e32 v196, v86, v196
	v_add_f32_e32 v197, v87, v197
	s_waitcnt lgkmcnt(3)
	v_mfma_f32_32x32x16_bf16 v[98:113], v[172:175], v[116:119], 0
	v_exp_f32_e32 v68, v68
	v_exp_f32_e32 v69, v69
	s_waitcnt lgkmcnt(2)
	v_mfma_f32_32x32x16_bf16 v[212:227], v[176:179], v[116:119], 0
	ds_read_b128 v[172:175], v189
	ds_read_b128 v[176:179], v189 offset:12288
	v_cvt_pk_bf16_f32 v84, v86, v87
	v_add_f32_e32 v196, v88, v196
	v_add_f32_e32 v197, v89, v197
	v_exp_f32_e32 v70, v70
	s_waitcnt lgkmcnt(3)
	v_mfma_f32_32x32x16_bf16 v[98:113], v[200:203], v[120:123], v[98:113]
	s_mov_b32 m0, s10
	v_lshl_add_u64 v[192:193], v[166:167], 0, s[92:93]
	global_load_lds_dwordx4 v[192:193], off
	v_exp_f32_e32 v71, v71
	s_waitcnt lgkmcnt(2)
	v_mfma_f32_32x32x16_bf16 v[212:227], v[204:207], v[120:123], v[212:227]
	ds_read_b128 v[200:203], v190
	ds_read_b128 v[204:207], v190 offset:12288
	v_cvt_pk_bf16_f32 v85, v88, v89
	v_add_f32_e32 v196, v90, v196
	v_add_f32_e32 v197, v91, v197
	v_exp_f32_e32 v72, v72
	s_waitcnt lgkmcnt(3)
	v_mfma_f32_32x32x16_bf16 v[98:113], v[172:175], v[124:127], v[98:113]
	v_exp_f32_e32 v73, v73
	s_waitcnt lgkmcnt(2)
	v_mfma_f32_32x32x16_bf16 v[212:227], v[176:179], v[124:127], v[212:227]
	ds_read_b128 v[172:175], v187 offset:128
	ds_read_b128 v[176:179], v187 offset:12416
	v_cvt_pk_bf16_f32 v86, v90, v91
	v_add_f32_e32 v196, v92, v196
	v_add_f32_e32 v197, v93, v197
	v_exp_f32_e32 v74, v74
	s_waitcnt lgkmcnt(3)
	v_mfma_f32_32x32x16_bf16 v[98:113], v[200:203], v[128:131], v[98:113]
	s_add_i32 m0, s10, 0x400
	v_lshl_add_u64 v[192:193], v[168:169], 0, s[92:93]
	global_load_lds_dwordx4 v[192:193], off
	v_exp_f32_e32 v75, v75
	v_cvt_pk_bf16_f32 v87, v92, v93
	s_waitcnt lgkmcnt(2)
	v_mfma_f32_32x32x16_bf16 v[212:227], v[204:207], v[128:131], v[212:227]
	ds_read_b128 v[200:203], v188 offset:128
	ds_read_b128 v[204:207], v188 offset:12416
	v_add_f32_e32 v196, v94, v196
	v_add_f32_e32 v197, v95, v197
	v_exp_f32_e32 v76, v76
	s_waitcnt lgkmcnt(3)
	v_mfma_f32_32x32x16_bf16 v[98:113], v[172:175], v[132:135], v[98:113]
	v_exp_f32_e32 v77, v77
	v_cvt_pk_bf16_f32 v88, v94, v95
	s_waitcnt lgkmcnt(2)
	v_mfma_f32_32x32x16_bf16 v[212:227], v[176:179], v[132:135], v[212:227]
	ds_read_b128 v[172:175], v189 offset:128
	ds_read_b128 v[176:179], v189 offset:12416
	v_add_f32_e32 v196, v96, v196
	v_add_f32_e32 v197, v97, v197
	v_exp_f32_e32 v78, v78
	s_waitcnt lgkmcnt(3)
	v_mfma_f32_32x32x16_bf16 v[98:113], v[200:203], v[136:139], v[98:113]
	s_add_i32 m0, s10, 0x800
	v_lshl_add_u64 v[192:193], v[170:171], 0, s[92:93]
	global_load_lds_dwordx4 v[192:193], off
	v_exp_f32_e32 v79, v79
	v_cvt_pk_bf16_f32 v89, v96, v97
	s_waitcnt lgkmcnt(2)
	v_mfma_f32_32x32x16_bf16 v[212:227], v[204:207], v[136:139], v[212:227]
	ds_read_b128 v[200:203], v190 offset:128
	ds_read_b128 v[204:207], v190 offset:12416
	v_exp_f32_e32 v80, v80
	v_exp_f32_e32 v81, v81
	s_waitcnt lgkmcnt(3)
	v_mfma_f32_32x32x16_bf16 v[98:113], v[172:175], v[140:143], v[98:113]
	v_add_f32_e32 v196, v66, v196
	v_add_f32_e32 v197, v67, v197
	v_cvt_pk_bf16_f32 v66, v66, v67
	s_waitcnt lgkmcnt(2)
	v_mfma_f32_32x32x16_bf16 v[212:227], v[176:179], v[140:143], v[212:227]
	ds_read_b128 v[172:175], v187 offset:256
	ds_read_b128 v[176:179], v187 offset:12544
	v_permlane32_swap_b32_e32 v82, v84
	v_permlane32_swap_b32_e32 v83, v85
	v_permlane32_swap_b32_e32 v86, v88
	v_permlane32_swap_b32_e32 v87, v89
	s_waitcnt lgkmcnt(3)
	v_mfma_f32_32x32x16_bf16 v[98:113], v[200:203], v[144:147], v[98:113]
	s_mov_b64 s[22:23], 0x61e0c100
	s_mov_b32 m0, s11
	v_lshl_add_u64 v[192:193], v[164:165], 0, s[22:23]
	global_load_lds_dwordx4 v[192:193], off
	v_add_f32_e32 v196, v68, v196
	v_add_f32_e32 v197, v69, v197
	v_cvt_pk_bf16_f32 v67, v68, v69
	s_waitcnt lgkmcnt(2)
	v_mfma_f32_32x32x16_bf16 v[212:227], v[204:207], v[144:147], v[212:227]
	ds_read_b128 v[200:203], v188 offset:256
	ds_read_b128 v[204:207], v188 offset:12544
	v_add_f32_e32 v196, v70, v196
	v_add_f32_e32 v197, v71, v197
	v_cvt_pk_bf16_f32 v68, v70, v71
	v_add_f32_e32 v196, v72, v196
	s_waitcnt lgkmcnt(3)
	v_mfma_f32_32x32x16_bf16 v[98:113], v[172:175], v[152:155], v[98:113]
	ds_read_b64_tr_b16 v[228:229], v191 offset:0
	ds_read_b64_tr_b16 v[230:231], v191 offset:2048
	v_add_f32_e32 v197, v73, v197
	v_cvt_pk_bf16_f32 v69, v72, v73
	v_add_f32_e32 v196, v74, v196
	v_add_f32_e32 v197, v75, v197
	s_waitcnt lgkmcnt(4)
	v_mfma_f32_32x32x16_bf16 v[212:227], v[176:179], v[152:155], v[212:227]
	ds_read_b128 v[172:175], v189 offset:256
	ds_read_b128 v[176:179], v189 offset:12544
	ds_read_b64_tr_b16 v[232:233], v191 offset:4096
	ds_read_b64_tr_b16 v[234:235], v191 offset:6144
	v_cvt_pk_bf16_f32 v70, v74, v75
	v_add_f32_e32 v196, v76, v196
	v_add_f32_e32 v197, v77, v197
	s_waitcnt lgkmcnt(7)
; #define SBAR() __builtin_amdgcn_sched_barrier(0)
; __device__ __forceinline__ void partialSM_fix(f32x16& p0, f32x16& p1) {
; #pragma unroll
;   for (int r = 0; r < 16; ++r) p0[r] = __builtin_amdgcn_exp2f(p0[r]);
; }
; __device__ __forceinline__ void finishSM_fix(f32x16& p0, f32x16& p1, float& l_lane, bf16x8& pa0, bf16x8& pa1, bf16x8& pa2, bf16x8& pa3) {
; #pragma unroll
;   for (int r = 0; r < 16; ++r) p1[r] = __builtin_amdgcn_exp2f(p1[r]);
;   float ps = 0;
; #pragma unroll
;   for (int r = 0; r < 16; ++r) ps += p0[r];
; #pragma unroll
;   for (int r = 0; r < 16; ++r) ps += p1[r];
;   l_lane += ps;
;     ...
;   PK4(p0, 0, pa0); PK4(p0, 8, pa1); PK4(p1, 0, pa2); PK4(p1, 8, pa3);
; template <int OFF> __device__ __forceinline__ s16x4 tr_read(int vb) {
;   s16x4 r; asm volatile("ds_read_b64_tr_b16 %0, %1 offset:%2" : "=&v"(r) : "v"(vb), "i"(OFF) : "memory"); return r;
; }
; template <int D0> __device__ __forceinline__ void pv_one(f32x16& od, int vb, bf16x8 pa0, bf16x8 pa1, bf16x8 pa2, bf16x8 pa3) {
;   const s16x4 l0 = tr_read<v_rd_off(D0, 0, 0)>(vb), h0 = tr_read<v_rd_off(D0, 0, 1)>(vb), l1 = tr_read<v_rd_off(D0, 1, 0)>(vb), h1 = tr_read<v_rd_off(D0, 1, 1)>(vb);
;   const s16x4 l2 = tr_read<v_rd_off(D0, 2, 0)>(vb), h2 = tr_read<v_rd_off(D0, 2, 1)>(vb), l3 = tr_read<v_rd_off(D0, 3, 0)>(vb), h3 = tr_read<v_rd_off(D0, 3, 1)>(vb);
;   asm volatile("s_waitcnt lgkmcnt(0)" ::: "memory"); SBAR();
;     ...
;   od = __builtin_amdgcn_mfma_f32_32x32x16_bf16(pa0, PK(l0, h0), od, 0, 0, 0);
;   od = __builtin_amdgcn_mfma_f32_32x32x16_bf16(pa1, PK(l1, h1), od, 0, 0, 0);
;   od = __builtin_amdgcn_mfma_f32_32x32x16_bf16(pa2, PK(l2, h2), od, 0, 0, 0);
;   od = __builtin_amdgcn_mfma_f32_32x32x16_bf16(pa3, PK(l3, h3), od, 0, 0, 0);
;     ...
; }
; __device__ __forceinline__ void pv_d0(f32x16 (&o)[4], int vb, bf16x8 pa0, bf16x8 pa1, bf16x8 pa2, bf16x8 pa3) {
;   pv_one<0>(o[0], vb, pa0, pa1, pa2, pa3); pv_one<1>(o[1], vb, pa0, pa1, pa2, pa3); pv_one<2>(o[2], vb, pa0, pa1, pa2, pa3); pv_one<3>(o[3], vb, pa0, pa1, pa2, pa3);
; }
	v_mfma_f32_32x32x16_bf16 v[98:113], v[200:203], v[148:151], v[98:113]
	ds_read_b64_tr_b16 v[236:237], v191 offset:8192
	ds_read_b64_tr_b16 v[238:239], v191 offset:10240
	s_mov_b64 s[22:23], 0x61e0c180
	s_add_i32 m0, s11, 0x400
	v_lshl_add_u64 v[192:193], v[164:165], 0, s[22:23]
	global_load_lds_dwordx4 v[192:193], off
	v_cvt_pk_bf16_f32 v71, v76, v77
	v_add_f32_e32 v196, v78, v196
	v_add_f32_e32 v197, v79, v197
	v_cvt_pk_bf16_f32 v72, v78, v79
	s_waitcnt lgkmcnt(8)
	v_mfma_f32_32x32x16_bf16 v[212:227], v[204:207], v[148:151], v[212:227]
	ds_read_b128 v[200:203], v190 offset:256
	ds_read_b128 v[204:207], v190 offset:12544
	ds_read_b64_tr_b16 v[240:241], v191 offset:12288
	ds_read_b64_tr_b16 v[242:243], v191 offset:14336
	v_add_f32_e32 v196, v80, v196
	v_add_f32_e32 v197, v81, v197
	v_cvt_pk_bf16_f32 v73, v80, v81
	s_waitcnt lgkmcnt(9)
	v_mfma_f32_32x32x16_bf16 v[98:113], v[172:175], v[160:163], v[98:113]
	ds_read_b64_tr_b16 v[246:247], v191 offset:512
	ds_read_b64_tr_b16 v[248:249], v191 offset:2560
	v_add_f32_e32 v196, v196, v197
	s_nop 0
	v_permlane32_swap_b32_e32 v66, v68
	v_permlane32_swap_b32_e32 v67, v69
	s_waitcnt lgkmcnt(10)
	v_mfma_f32_32x32x16_bf16 v[212:227], v[176:179], v[160:163], v[212:227]
	ds_read_b64_tr_b16 v[250:251], v191 offset:4608
	ds_read_b64_tr_b16 v[252:253], v191 offset:6656
	v_permlane32_swap_b32_e32 v70, v72
	v_permlane32_swap_b32_e32 v71, v73
	v_add_f32_e32 v114, v114, v196
	s_waitcnt lgkmcnt(7)
	v_mfma_f32_32x32x16_bf16 v[98:113], v[200:203], v[156:159], v[98:113]
	s_waitcnt lgkmcnt(6)
	v_mfma_f32_32x32x16_bf16 v[212:227], v[204:207], v[156:159], v[212:227]
	v_mfma_f32_32x32x16_bf16 v[2:17], v[82:85], v[228:231], v[2:17]
	ds_read_b64_tr_b16 v[228:229], v191 offset:8704
	ds_read_b64_tr_b16 v[230:231], v191 offset:10752
	v_mfma_f32_32x32x16_bf16 v[2:17], v[86:89], v[232:235], v[2:17]
	ds_read_b64_tr_b16 v[232:233], v191 offset:12800
	ds_read_b64_tr_b16 v[234:235], v191 offset:14848
	v_mfma_f32_32x32x16_bf16 v[2:17], v[66:69], v[236:239], v[2:17]
	ds_read_b64_tr_b16 v[236:237], v191 offset:1024
	ds_read_b64_tr_b16 v[238:239], v191 offset:3072
	s_waitcnt lgkmcnt(10)
	v_mfma_f32_32x32x16_bf16 v[2:17], v[70:73], v[240:243], v[2:17]
	ds_read_b64_tr_b16 v[240:241], v191 offset:5120
	ds_read_b64_tr_b16 v[242:243], v191 offset:7168
	v_exp_f32_e32 v98, v98
	s_waitcnt lgkmcnt(10)
	v_mfma_f32_32x32x16_bf16 v[18:33], v[82:85], v[246:249], v[18:33]
	ds_read_b64_tr_b16 v[246:247], v191 offset:9216
	ds_read_b64_tr_b16 v[248:249], v191 offset:11264
	v_exp_f32_e32 v99, v99
	s_waitcnt lgkmcnt(10)
	v_mfma_f32_32x32x16_bf16 v[18:33], v[86:89], v[250:253], v[18:33]
	ds_read_b64_tr_b16 v[250:251], v191 offset:13312
	ds_read_b64_tr_b16 v[252:253], v191 offset:15360
	v_exp_f32_e32 v100, v100
	s_waitcnt lgkmcnt(10)
	v_mfma_f32_32x32x16_bf16 v[18:33], v[66:69], v[228:231], v[18:33]
	ds_read_b64_tr_b16 v[228:229], v191 offset:1536
	ds_read_b64_tr_b16 v[230:231], v191 offset:3584
	v_exp_f32_e32 v101, v101
	s_waitcnt lgkmcnt(10)
	v_mfma_f32_32x32x16_bf16 v[18:33], v[70:73], v[232:235], v[18:33]
	ds_read_b64_tr_b16 v[232:233], v191 offset:5632
	ds_read_b64_tr_b16 v[234:235], v191 offset:7680
	v_exp_f32_e32 v102, v102
	s_waitcnt lgkmcnt(10)
	v_mfma_f32_32x32x16_bf16 v[34:49], v[82:85], v[236:239], v[34:49]
	ds_read_b64_tr_b16 v[236:237], v191 offset:9728
	ds_read_b64_tr_b16 v[238:239], v191 offset:11776
	v_exp_f32_e32 v103, v103
	s_waitcnt lgkmcnt(10)
	v_mfma_f32_32x32x16_bf16 v[34:49], v[86:89], v[240:243], v[34:49]
	ds_read_b64_tr_b16 v[240:241], v191 offset:13824
	ds_read_b64_tr_b16 v[242:243], v191 offset:15872
	v_exp_f32_e32 v104, v104
	s_waitcnt lgkmcnt(10)
	v_mfma_f32_32x32x16_bf16 v[34:49], v[66:69], v[246:249], v[34:49]
	v_exp_f32_e32 v105, v105
	s_waitcnt lgkmcnt(8)
	v_mfma_f32_32x32x16_bf16 v[34:49], v[70:73], v[250:253], v[34:49]
	v_exp_f32_e32 v106, v106
	s_waitcnt lgkmcnt(6)
	v_mfma_f32_32x32x16_bf16 v[50:65], v[82:85], v[228:231], v[50:65]
	v_exp_f32_e32 v107, v107
	v_exp_f32_e32 v108, v108
	s_waitcnt lgkmcnt(4)
	v_mfma_f32_32x32x16_bf16 v[50:65], v[86:89], v[232:235], v[50:65]
	v_exp_f32_e32 v109, v109
	v_exp_f32_e32 v110, v110
	s_waitcnt lgkmcnt(2)
	v_mfma_f32_32x32x16_bf16 v[50:65], v[66:69], v[236:239], v[50:65]
	v_exp_f32_e32 v111, v111
	v_exp_f32_e32 v112, v112
	s_waitcnt lgkmcnt(0)
	v_mfma_f32_32x32x16_bf16 v[50:65], v[70:73], v[240:243], v[50:65]
	v_exp_f32_e32 v113, v113
	s_waitcnt vmcnt(5)
	s_barrier
; __device__ __forceinline__ void finishSM_fix(f32x16& p0, f32x16& p1, float& l_lane, bf16x8& pa0, bf16x8& pa1, bf16x8& pa2, bf16x8& pa3) {
; #pragma unroll
;   for (int r = 0; r < 16; ++r) p1[r] = __builtin_amdgcn_exp2f(p1[r]);
;   float ps = 0;
; #pragma unroll
;   for (int r = 0; r < 16; ++r) ps += p0[r];
; #pragma unroll
;   for (int r = 0; r < 16; ++r) ps += p1[r];
;   l_lane += ps;
;     ...
;   PK4(p0, 0, pa0); PK4(p0, 8, pa1); PK4(p1, 0, pa2); PK4(p1, 8, pa3);
; __device__ __forceinline__ void qkt12(f32x16& p0, f32x16& p1, const char* Ks, const bf16x8 (&qr)[12], const int (&kb)[4]) {
;   p0 = f32x16{}; p1 = f32x16{};
;     ...
;   bf16x8 c0 = KLD(0, 0), c1 = KLD(0, 1);
; #pragma unroll
;   for (int d0 = 0; d0 < 12; ++d0) {
;     bf16x8 n0 = c0, n1 = c1;
;     if (d0 < 11) { n0 = KLD(d0 + 1, 0); n1 = KLD(d0 + 1, 1); }
;     __builtin_amdgcn_sched_group_barrier(0x100, 2, 0);
;     p0 = __builtin_amdgcn_mfma_f32_32x32x16_bf16(c0, qr[d0], p0, 0, 0, 0);
;     p1 = __builtin_amdgcn_mfma_f32_32x32x16_bf16(c1, qr[d0], p1, 0, 0, 0);
;     __builtin_amdgcn_sched_group_barrier(0x008, 2, 0);
;     c0 = n0; c1 = n1; }
;     ...
; }
	s_mul_i32 s6, s25, 0x6000
	s_mul_i32 s10, s24, 0x6000
	s_lshl_b32 s11, s26, 14
	s_add_i32 s10, s43, s10
	s_add_i32 s11, s52, s11
	v_add_u32_e32 v187, s6, v183
	v_add_u32_e32 v188, s6, v184
	v_add_u32_e32 v189, s6, v185
	v_add_u32_e32 v190, s6, v186
	v_lshl_add_u32 v191, s24, 14, v182
	ds_read_b128 v[172:175], v187
	ds_read_b128 v[176:179], v187 offset:12288
	ds_read_b128 v[200:203], v188
	ds_read_b128 v[204:207], v188 offset:12288
	v_add_f32_e32 v196, v98, v99
	v_cvt_pk_bf16_f32 v98, v98, v99
	v_add_f32_e32 v197, v100, v101
	v_exp_f32_e32 v212, v212
	v_exp_f32_e32 v213, v213
	v_cvt_pk_bf16_f32 v99, v100, v101
	v_add_f32_e32 v196, v102, v196
	v_add_f32_e32 v197, v103, v197
	s_waitcnt lgkmcnt(3)
	v_mfma_f32_32x32x16_bf16 v[82:97], v[172:175], v[116:119], 0
	v_exp_f32_e32 v214, v214
	v_exp_f32_e32 v215, v215
	s_waitcnt lgkmcnt(2)
	v_mfma_f32_32x32x16_bf16 v[66:81], v[176:179], v[116:119], 0
	ds_read_b128 v[172:175], v189
	ds_read_b128 v[176:179], v189 offset:12288
	v_cvt_pk_bf16_f32 v100, v102, v103
	v_add_f32_e32 v196, v104, v196
	v_add_f32_e32 v197, v105, v197
	v_exp_f32_e32 v216, v216
	s_waitcnt lgkmcnt(3)
	v_mfma_f32_32x32x16_bf16 v[82:97], v[200:203], v[120:123], v[82:97]
	s_mov_b32 m0, s10
	v_lshl_add_u64 v[192:193], v[166:167], 0, s[94:95]
	global_load_lds_dwordx4 v[192:193], off
	v_exp_f32_e32 v217, v217
	s_waitcnt lgkmcnt(2)
	v_mfma_f32_32x32x16_bf16 v[66:81], v[204:207], v[120:123], v[66:81]
	ds_read_b128 v[200:203], v190
	ds_read_b128 v[204:207], v190 offset:12288
	v_cvt_pk_bf16_f32 v101, v104, v105
	v_add_f32_e32 v196, v106, v196
	v_add_f32_e32 v197, v107, v197
	v_exp_f32_e32 v218, v218
	s_waitcnt lgkmcnt(3)
	v_mfma_f32_32x32x16_bf16 v[82:97], v[172:175], v[124:127], v[82:97]
	v_exp_f32_e32 v219, v219
	s_waitcnt lgkmcnt(2)
	v_mfma_f32_32x32x16_bf16 v[66:81], v[176:179], v[124:127], v[66:81]
	ds_read_b128 v[172:175], v187 offset:128
	ds_read_b128 v[176:179], v187 offset:12416
	v_cvt_pk_bf16_f32 v102, v106, v107
	v_add_f32_e32 v196, v108, v196
	v_add_f32_e32 v197, v109, v197
	v_exp_f32_e32 v220, v220
	s_waitcnt lgkmcnt(3)
	v_mfma_f32_32x32x16_bf16 v[82:97], v[200:203], v[128:131], v[82:97]
	s_add_i32 m0, s10, 0x400
	v_lshl_add_u64 v[192:193], v[168:169], 0, s[94:95]
	global_load_lds_dwordx4 v[192:193], off
	v_exp_f32_e32 v221, v221
	v_cvt_pk_bf16_f32 v103, v108, v109
	s_waitcnt lgkmcnt(2)
	v_mfma_f32_32x32x16_bf16 v[66:81], v[204:207], v[128:131], v[66:81]
	ds_read_b128 v[200:203], v188 offset:128
	ds_read_b128 v[204:207], v188 offset:12416
	v_add_f32_e32 v196, v110, v196
	v_add_f32_e32 v197, v111, v197
	v_exp_f32_e32 v222, v222
	s_waitcnt lgkmcnt(3)
	v_mfma_f32_32x32x16_bf16 v[82:97], v[172:175], v[132:135], v[82:97]
	v_exp_f32_e32 v223, v223
	v_cvt_pk_bf16_f32 v104, v110, v111
	s_waitcnt lgkmcnt(2)
	v_mfma_f32_32x32x16_bf16 v[66:81], v[176:179], v[132:135], v[66:81]
	ds_read_b128 v[172:175], v189 offset:128
	ds_read_b128 v[176:179], v189 offset:12416
	v_add_f32_e32 v196, v112, v196
	v_add_f32_e32 v197, v113, v197
	v_exp_f32_e32 v224, v224
	s_waitcnt lgkmcnt(3)
	v_mfma_f32_32x32x16_bf16 v[82:97], v[200:203], v[136:139], v[82:97]
	s_add_i32 m0, s10, 0x800
	v_lshl_add_u64 v[192:193], v[170:171], 0, s[94:95]
	global_load_lds_dwordx4 v[192:193], off
	v_exp_f32_e32 v225, v225
	v_cvt_pk_bf16_f32 v105, v112, v113
	s_waitcnt lgkmcnt(2)
	v_mfma_f32_32x32x16_bf16 v[66:81], v[204:207], v[136:139], v[66:81]
	ds_read_b128 v[200:203], v190 offset:128
	ds_read_b128 v[204:207], v190 offset:12416
	v_exp_f32_e32 v226, v226
	v_exp_f32_e32 v227, v227
	s_waitcnt lgkmcnt(3)
	v_mfma_f32_32x32x16_bf16 v[82:97], v[172:175], v[140:143], v[82:97]
	v_add_f32_e32 v196, v212, v196
	v_add_f32_e32 v197, v213, v197
	v_cvt_pk_bf16_f32 v212, v212, v213
	s_waitcnt lgkmcnt(2)
	v_mfma_f32_32x32x16_bf16 v[66:81], v[176:179], v[140:143], v[66:81]
	ds_read_b128 v[172:175], v187 offset:256
	ds_read_b128 v[176:179], v187 offset:12544
	v_permlane32_swap_b32_e32 v98, v100
	v_permlane32_swap_b32_e32 v99, v101
	v_permlane32_swap_b32_e32 v102, v104
	v_permlane32_swap_b32_e32 v103, v105
	s_waitcnt lgkmcnt(3)
	v_mfma_f32_32x32x16_bf16 v[82:97], v[200:203], v[144:147], v[82:97]
	s_mov_b64 s[22:23], 0x61e8c100
	s_mov_b32 m0, s11
	v_lshl_add_u64 v[192:193], v[164:165], 0, s[22:23]
	global_load_lds_dwordx4 v[192:193], off
	v_add_f32_e32 v196, v214, v196
	v_add_f32_e32 v197, v215, v197
	v_cvt_pk_bf16_f32 v213, v214, v215
	s_waitcnt lgkmcnt(2)
	v_mfma_f32_32x32x16_bf16 v[66:81], v[204:207], v[144:147], v[66:81]
	ds_read_b128 v[200:203], v188 offset:256
	ds_read_b128 v[204:207], v188 offset:12544
	v_add_f32_e32 v196, v216, v196
	v_add_f32_e32 v197, v217, v197
	v_cvt_pk_bf16_f32 v214, v216, v217
	v_add_f32_e32 v196, v218, v196
	s_waitcnt lgkmcnt(3)
	v_mfma_f32_32x32x16_bf16 v[82:97], v[172:175], v[152:155], v[82:97]
	ds_read_b64_tr_b16 v[228:229], v191 offset:0
	ds_read_b64_tr_b16 v[230:231], v191 offset:2048
	v_add_f32_e32 v197, v219, v197
	v_cvt_pk_bf16_f32 v215, v218, v219
	v_add_f32_e32 v196, v220, v196
	v_add_f32_e32 v197, v221, v197
	s_waitcnt lgkmcnt(4)
	v_mfma_f32_32x32x16_bf16 v[66:81], v[176:179], v[152:155], v[66:81]
	ds_read_b128 v[172:175], v189 offset:256
	ds_read_b128 v[176:179], v189 offset:12544
	ds_read_b64_tr_b16 v[232:233], v191 offset:4096
	ds_read_b64_tr_b16 v[234:235], v191 offset:6144
	v_cvt_pk_bf16_f32 v216, v220, v221
	v_add_f32_e32 v196, v222, v196
	v_add_f32_e32 v197, v223, v197
	s_waitcnt lgkmcnt(7)
; #define SBAR() __builtin_amdgcn_sched_barrier(0)
; #define TOP(t, st) do { if ((t) + 2 < NT) asm volatile("s_waitcnt vmcnt(5)" ::: "memory"); else asm volatile("s_waitcnt vmcnt(0)" ::: "memory"); \
;     __builtin_amdgcn_s_barrier(); asm volatile("" ::: "memory"); \
;     if ((t) + 2 < NT) KDMA((t) + 2, NEXT3(NEXT3(st))); if ((t) + 1 < NT) VDMA((t) + 1, NEXT3(st)); } while (0)
; template <int OFF> __device__ __forceinline__ s16x4 tr_read(int vb) {
;   s16x4 r; asm volatile("ds_read_b64_tr_b16 %0, %1 offset:%2" : "=&v"(r) : "v"(vb), "i"(OFF) : "memory"); return r;
; }
; template <int D0> __device__ __forceinline__ void pv_one(f32x16& od, int vb, bf16x8 pa0, bf16x8 pa1, bf16x8 pa2, bf16x8 pa3) {
;   const s16x4 l0 = tr_read<v_rd_off(D0, 0, 0)>(vb), h0 = tr_read<v_rd_off(D0, 0, 1)>(vb), l1 = tr_read<v_rd_off(D0, 1, 0)>(vb), h1 = tr_read<v_rd_off(D0, 1, 1)>(vb);
;   const s16x4 l2 = tr_read<v_rd_off(D0, 2, 0)>(vb), h2 = tr_read<v_rd_off(D0, 2, 1)>(vb), l3 = tr_read<v_rd_off(D0, 3, 0)>(vb), h3 = tr_read<v_rd_off(D0, 3, 1)>(vb);
;   asm volatile("s_waitcnt lgkmcnt(0)" ::: "memory"); SBAR();
;     ...
;   od = __builtin_amdgcn_mfma_f32_32x32x16_bf16(pa0, PK(l0, h0), od, 0, 0, 0);
;   od = __builtin_amdgcn_mfma_f32_32x32x16_bf16(pa1, PK(l1, h1), od, 0, 0, 0);
;   od = __builtin_amdgcn_mfma_f32_32x32x16_bf16(pa2, PK(l2, h2), od, 0, 0, 0);
;   od = __builtin_amdgcn_mfma_f32_32x32x16_bf16(pa3, PK(l3, h3), od, 0, 0, 0);
;     ...
; }
; __device__ __forceinline__ void pv_d0(f32x16 (&o)[4], int vb, bf16x8 pa0, bf16x8 pa1, bf16x8 pa2, bf16x8 pa3) {
;   pv_one<0>(o[0], vb, pa0, pa1, pa2, pa3); pv_one<1>(o[1], vb, pa0, pa1, pa2, pa3); pv_one<2>(o[2], vb, pa0, pa1, pa2, pa3); pv_one<3>(o[3], vb, pa0, pa1, pa2, pa3);
; }
; __device__ __forceinline__ void attn_unit_dma(const bf16_t* __restrict__ Qb, const bf16_t* __restrict__ Kh, const bf16_t* __restrict__ Vh, int seq, char* lds, LAS unsigned char* ldsl, ...
;     ...
;     sp = st; st = NEXT3(st);
;     TOP(j + 1, st);
;     SBAR(); qkt12(pA0, pA1, lds + DMA_KRING + st * SHM_K, qr, kb);
;     finishSM_fix(pB0, pB1, l_reg, pa0, pa1, pa2, pa3); SBAR();
;     pv_d0(o, vb0 + sp * SHM_V, pa0, pa1, pa2, pa3); partialSM_fix(pA0, pA1);
;   }
	v_mfma_f32_32x32x16_bf16 v[82:97], v[200:203], v[148:151], v[82:97]
	ds_read_b64_tr_b16 v[236:237], v191 offset:8192
	ds_read_b64_tr_b16 v[238:239], v191 offset:10240
	s_mov_b64 s[22:23], 0x61e8c180
	s_add_i32 m0, s11, 0x400
	v_lshl_add_u64 v[192:193], v[164:165], 0, s[22:23]
	global_load_lds_dwordx4 v[192:193], off
	v_cvt_pk_bf16_f32 v217, v222, v223
	v_add_f32_e32 v196, v224, v196
	v_add_f32_e32 v197, v225, v197
	v_cvt_pk_bf16_f32 v218, v224, v225
	s_waitcnt lgkmcnt(8)
	v_mfma_f32_32x32x16_bf16 v[66:81], v[204:207], v[148:151], v[66:81]
	ds_read_b128 v[200:203], v190 offset:256
	ds_read_b128 v[204:207], v190 offset:12544
	ds_read_b64_tr_b16 v[240:241], v191 offset:12288
	ds_read_b64_tr_b16 v[242:243], v191 offset:14336
	v_add_f32_e32 v196, v226, v196
	v_add_f32_e32 v197, v227, v197
	v_cvt_pk_bf16_f32 v219, v226, v227
	s_waitcnt lgkmcnt(9)
	v_mfma_f32_32x32x16_bf16 v[82:97], v[172:175], v[160:163], v[82:97]
	ds_read_b64_tr_b16 v[246:247], v191 offset:512
	ds_read_b64_tr_b16 v[248:249], v191 offset:2560
	v_add_f32_e32 v196, v196, v197
	s_nop 0
	v_permlane32_swap_b32_e32 v212, v214
	v_permlane32_swap_b32_e32 v213, v215
	s_waitcnt lgkmcnt(10)
	v_mfma_f32_32x32x16_bf16 v[66:81], v[176:179], v[160:163], v[66:81]
	ds_read_b64_tr_b16 v[250:251], v191 offset:4608
	ds_read_b64_tr_b16 v[252:253], v191 offset:6656
	v_permlane32_swap_b32_e32 v216, v218
	v_permlane32_swap_b32_e32 v217, v219
	v_add_f32_e32 v114, v114, v196
	s_waitcnt lgkmcnt(7)
	v_mfma_f32_32x32x16_bf16 v[82:97], v[200:203], v[156:159], v[82:97]
	s_waitcnt lgkmcnt(6)
	v_mfma_f32_32x32x16_bf16 v[66:81], v[204:207], v[156:159], v[66:81]
	v_mfma_f32_32x32x16_bf16 v[2:17], v[98:101], v[228:231], v[2:17]
	ds_read_b64_tr_b16 v[228:229], v191 offset:8704
	ds_read_b64_tr_b16 v[230:231], v191 offset:10752
	v_mfma_f32_32x32x16_bf16 v[2:17], v[102:105], v[232:235], v[2:17]
	ds_read_b64_tr_b16 v[232:233], v191 offset:12800
	ds_read_b64_tr_b16 v[234:235], v191 offset:14848
	v_mfma_f32_32x32x16_bf16 v[2:17], v[212:215], v[236:239], v[2:17]
	ds_read_b64_tr_b16 v[236:237], v191 offset:1024
	ds_read_b64_tr_b16 v[238:239], v191 offset:3072
	v_lshl_add_u64 v[166:167], v[166:167], 0, s[90:91]
	s_waitcnt lgkmcnt(10)
	v_mfma_f32_32x32x16_bf16 v[2:17], v[216:219], v[240:243], v[2:17]
	ds_read_b64_tr_b16 v[240:241], v191 offset:5120
	ds_read_b64_tr_b16 v[242:243], v191 offset:7168
	v_exp_f32_e32 v82, v82
	v_lshl_add_u64 v[168:169], v[168:169], 0, s[90:91]
	s_waitcnt lgkmcnt(10)
	v_mfma_f32_32x32x16_bf16 v[18:33], v[98:101], v[246:249], v[18:33]
	ds_read_b64_tr_b16 v[246:247], v191 offset:9216
	ds_read_b64_tr_b16 v[248:249], v191 offset:11264
	v_exp_f32_e32 v83, v83
	v_lshl_add_u64 v[170:171], v[170:171], 0, s[90:91]
	s_waitcnt lgkmcnt(10)
	v_mfma_f32_32x32x16_bf16 v[18:33], v[102:105], v[250:253], v[18:33]
	ds_read_b64_tr_b16 v[250:251], v191 offset:13312
	ds_read_b64_tr_b16 v[252:253], v191 offset:15360
	v_exp_f32_e32 v84, v84
	v_lshl_add_u64 v[164:165], v[164:165], 0, s[68:69]
	s_waitcnt lgkmcnt(10)
	v_mfma_f32_32x32x16_bf16 v[18:33], v[212:215], v[228:231], v[18:33]
	ds_read_b64_tr_b16 v[228:229], v191 offset:1536
	ds_read_b64_tr_b16 v[230:231], v191 offset:3584
	v_exp_f32_e32 v85, v85
	s_waitcnt lgkmcnt(10)
	v_mfma_f32_32x32x16_bf16 v[18:33], v[216:219], v[232:235], v[18:33]
	ds_read_b64_tr_b16 v[232:233], v191 offset:5632
	ds_read_b64_tr_b16 v[234:235], v191 offset:7680
	v_exp_f32_e32 v86, v86
	s_waitcnt lgkmcnt(10)
	v_mfma_f32_32x32x16_bf16 v[34:49], v[98:101], v[236:239], v[34:49]
	ds_read_b64_tr_b16 v[236:237], v191 offset:9728
	ds_read_b64_tr_b16 v[238:239], v191 offset:11776
	v_exp_f32_e32 v87, v87
	s_waitcnt lgkmcnt(10)
	v_mfma_f32_32x32x16_bf16 v[34:49], v[102:105], v[240:243], v[34:49]
	ds_read_b64_tr_b16 v[240:241], v191 offset:13824
	ds_read_b64_tr_b16 v[242:243], v191 offset:15872
	v_exp_f32_e32 v88, v88
	s_waitcnt lgkmcnt(10)
	v_mfma_f32_32x32x16_bf16 v[34:49], v[212:215], v[246:249], v[34:49]
	v_exp_f32_e32 v89, v89
	s_waitcnt lgkmcnt(8)
	v_mfma_f32_32x32x16_bf16 v[34:49], v[216:219], v[250:253], v[34:49]
	v_exp_f32_e32 v90, v90
	s_waitcnt lgkmcnt(6)
	v_mfma_f32_32x32x16_bf16 v[50:65], v[98:101], v[228:231], v[50:65]
	v_exp_f32_e32 v91, v91
	v_exp_f32_e32 v92, v92
	s_waitcnt lgkmcnt(4)
	v_mfma_f32_32x32x16_bf16 v[50:65], v[102:105], v[232:235], v[50:65]
	v_exp_f32_e32 v93, v93
	v_exp_f32_e32 v94, v94
	s_waitcnt lgkmcnt(2)
	v_mfma_f32_32x32x16_bf16 v[50:65], v[212:215], v[236:239], v[50:65]
	v_exp_f32_e32 v95, v95
	v_exp_f32_e32 v96, v96
	s_waitcnt lgkmcnt(0)
	v_mfma_f32_32x32x16_bf16 v[50:65], v[216:219], v[240:243], v[50:65]
	v_exp_f32_e32 v97, v97
	s_mov_b32 s26, s25
	s_add_i32 s72, s72, 2
	s_cmp_lt_u32 s72, s37
	s_cbranch_scc1 .Lfa_loop
	v_mov_b32_e32 v195, v82
	v_mov_b32_e32 v216, v83
	v_mov_b32_e32 v213, v84
	v_mov_b32_e32 v215, v85
	v_mov_b32_e32 v197, v86
	v_mov_b32_e32 v214, v87
	v_mov_b32_e32 v196, v88
	v_mov_b32_e32 v212, v89
	v_mov_b32_e32 v191, v90
	v_mov_b32_e32 v193, v91
	v_mov_b32_e32 v189, v92
	v_mov_b32_e32 v192, v93
	v_mov_b32_e32 v188, v94
	v_mov_b32_e32 v190, v95
	v_mov_b32_e32 v187, v96
	v_mov_b32_e32 v194, v97
	s_branch .LBB0_853
	s_nop 0
	s_nop 0
	s_nop 0
	s_nop 0
	s_nop 0
	s_nop 0
	s_nop 0
	s_nop 0
